# speedup vs baseline: 1.0072x; 1.0072x over previous
.LBB0_1081:
	s_or_b64 exec, exec, s[0:1]
	v_mov_b32_e32 v197, v244
	v_mov_b32_e32 v166, 0
	v_ashrrev_i32_e32 v128, 2, v197
	v_and_b32_e32 v149, 0xffffffc0, v128
	v_and_b32_e32 v145, 15, v197
	v_add_u32_e32 v128, s50, v149
	v_or_b32_e32 v136, v128, v145
	v_mov_b32_e32 v242, v136
	v_ashrrev_i32_e32 v243, 31, v136
	v_lshl_add_u64 v[242:243], v[242:243], 2, s[68:69]
	global_load_dword v234, v[242:243], off
	global_load_dword v235, v[242:243], off offset:64
	global_load_dword v236, v[242:243], off offset:128
	global_load_dword v237, v[242:243], off offset:192
	global_load_dword v238, v[242:243], off offset:512
	global_load_dword v239, v[242:243], off offset:576
	global_load_dword v240, v[242:243], off offset:640
	global_load_dword v241, v[242:243], off offset:704
	s_waitcnt vmcnt(0)
	v_cmp_gt_i32_e64 s[16:17], s79, v136
	v_mov_b32_e32 v170, 0
	s_and_saveexec_b64 s[0:1], s[16:17]
	s_cbranch_execz .LBB0_1083
	v_ashrrev_i32_e32 v137, 31, v136
	v_fmamk_f32 v128, v234, 0x39800000, v195
	v_mul_f32_e32 v129, 0x4b800000, v128
	v_cmp_gt_f32_e32 vcc, s80, v128
	s_nop 1
	v_cndmask_b32_e32 v128, v128, v129, vcc
	v_rsq_f32_e32 v128, v128
	s_nop 0
	v_mul_f32_e32 v129, 0x45800000, v128
	v_cndmask_b32_e32 v170, v128, v129, vcc
.LBB0_1083:
	s_or_b64 exec, exec, s[0:1]
	v_or_b32_e32 v168, 16, v136
	v_cmp_gt_i32_e64 s[14:15], s79, v168
	s_and_saveexec_b64 s[0:1], s[14:15]
	s_cbranch_execz .LBB0_1085
	v_ashrrev_i32_e32 v169, 31, v168
	v_fmamk_f32 v128, v235, 0x39800000, v195
	v_mul_f32_e32 v129, 0x4b800000, v128
	v_cmp_gt_f32_e32 vcc, s80, v128
	s_nop 1
	v_cndmask_b32_e32 v128, v128, v129, vcc
	v_rsq_f32_e32 v128, v128
	s_nop 0
	v_mul_f32_e32 v129, 0x45800000, v128
	v_cndmask_b32_e32 v166, v128, v129, vcc
.LBB0_1085:
	s_or_b64 exec, exec, s[0:1]
	v_or_b32_e32 v164, 32, v136
	v_cmp_gt_i32_e64 s[12:13], s79, v164
	v_mov_b32_e32 v156, 0
	v_mov_b32_e32 v160, 0
	s_and_saveexec_b64 s[0:1], s[12:13]
	s_cbranch_execz .LBB0_1087
	v_ashrrev_i32_e32 v165, 31, v164
	v_fmamk_f32 v128, v236, 0x39800000, v195
	v_mul_f32_e32 v129, 0x4b800000, v128
	v_cmp_gt_f32_e32 vcc, s80, v128
	s_nop 1
	v_cndmask_b32_e32 v128, v128, v129, vcc
	v_rsq_f32_e32 v128, v128
	s_nop 0
	v_mul_f32_e32 v129, 0x45800000, v128
	v_cndmask_b32_e32 v160, v128, v129, vcc
.LBB0_1087:
	s_or_b64 exec, exec, s[0:1]
	v_or_b32_e32 v158, 48, v136
	v_cmp_gt_i32_e64 s[10:11], s79, v158
	s_and_saveexec_b64 s[0:1], s[10:11]
	s_cbranch_execz .LBB0_1089
	v_ashrrev_i32_e32 v159, 31, v158
	v_fmamk_f32 v128, v237, 0x39800000, v195
	v_mul_f32_e32 v129, 0x4b800000, v128
	v_cmp_gt_f32_e32 vcc, s80, v128
	s_nop 1
	v_cndmask_b32_e32 v128, v128, v129, vcc
	v_rsq_f32_e32 v128, v128
	s_nop 0
	v_mul_f32_e32 v129, 0x45800000, v128
	v_cndmask_b32_e32 v156, v128, v129, vcc
.LBB0_1089:
	s_or_b64 exec, exec, s[0:1]
	v_add_u32_e32 v154, 0x80, v136
	v_cmp_gt_i32_e64 s[8:9], s81, v136
	v_mov_b32_e32 v148, 0
	v_mov_b32_e32 v152, 0
	s_and_saveexec_b64 s[0:1], s[8:9]
	s_cbranch_execz .LBB0_1091
	v_ashrrev_i32_e32 v155, 31, v154
	v_fmamk_f32 v128, v238, 0x39800000, v195
	v_mul_f32_e32 v129, 0x4b800000, v128
	v_cmp_gt_f32_e32 vcc, s80, v128
	s_nop 1
	v_cndmask_b32_e32 v128, v128, v129, vcc
	v_rsq_f32_e32 v128, v128
	s_nop 0
	v_mul_f32_e32 v129, 0x45800000, v128
	v_cndmask_b32_e32 v152, v128, v129, vcc
.LBB0_1091:
	s_or_b64 exec, exec, s[0:1]
	s_movk_i32 s0, 0x1fb0
	v_add_u32_e32 v150, 0x90, v136
	v_cmp_gt_i32_e64 s[6:7], s0, v136
	s_and_saveexec_b64 s[0:1], s[6:7]
	s_cbranch_execz .LBB0_1093
	v_ashrrev_i32_e32 v151, 31, v150
	v_fmamk_f32 v128, v239, 0x39800000, v195
	v_mul_f32_e32 v129, 0x4b800000, v128
	v_cmp_gt_f32_e32 vcc, s80, v128
	s_nop 1
	v_cndmask_b32_e32 v128, v128, v129, vcc
	v_rsq_f32_e32 v128, v128
	s_nop 0
	v_mul_f32_e32 v129, 0x45800000, v128
	v_cndmask_b32_e32 v148, v128, v129, vcc
.LBB0_1093:
	s_or_b64 exec, exec, s[0:1]
	s_movk_i32 s0, 0x1fa0
	v_add_u32_e32 v146, 0xa0, v136
	v_cmp_gt_i32_e64 s[4:5], s0, v136
	v_mov_b32_e32 v138, 0
	v_mov_b32_e32 v144, 0
	s_and_saveexec_b64 s[0:1], s[4:5]
	s_cbranch_execz .LBB0_1095
	v_ashrrev_i32_e32 v147, 31, v146
	v_fmamk_f32 v128, v240, 0x39800000, v195
	v_mul_f32_e32 v129, 0x4b800000, v128
	v_cmp_gt_f32_e32 vcc, s80, v128
	s_nop 1
	v_cndmask_b32_e32 v128, v128, v129, vcc
	v_rsq_f32_e32 v128, v128
	s_nop 0
	v_mul_f32_e32 v129, 0x45800000, v128
	v_cndmask_b32_e32 v144, v128, v129, vcc
.LBB0_1095:
	s_or_b64 exec, exec, s[0:1]
	s_movk_i32 s0, 0x1f90
	v_add_u32_e32 v142, 0xb0, v136
	v_cmp_gt_i32_e64 s[2:3], s0, v136
	s_and_saveexec_b64 s[0:1], s[2:3]
	s_cbranch_execz .LBB0_1097
	v_ashrrev_i32_e32 v143, 31, v142
	v_fmamk_f32 v128, v241, 0x39800000, v195
	v_mul_f32_e32 v129, 0x4b800000, v128
	v_cmp_gt_f32_e32 vcc, s80, v128
	s_nop 1
	v_cndmask_b32_e32 v128, v128, v129, vcc
	v_rsq_f32_e32 v128, v128
	s_nop 0
	v_mul_f32_e32 v129, 0x45800000, v128
	v_cndmask_b32_e32 v138, v128, v129, vcc

.LBB0_1422:
	s_or_b64 exec, exec, s[2:3]
	v_mov_b32_e32 v192, v244
	s_movk_i32 s1, 0x2040
	v_ashrrev_i32_e32 v128, 2, v192
	v_and_b32_e32 v149, 0xffffffc0, v128
	v_and_b32_e32 v145, 15, v192
	v_add_u32_e32 v128, s0, v149
	v_or_b32_e32 v136, v128, v145
	v_mov_b32_e32 v242, v136
	v_ashrrev_i32_e32 v243, 31, v136
	v_lshl_add_u64 v[242:243], v[242:243], 2, s[68:69]
	global_load_dword v234, v[242:243], off
	global_load_dword v235, v[242:243], off offset:64
	global_load_dword v236, v[242:243], off offset:128
	global_load_dword v237, v[242:243], off offset:192
	global_load_dword v238, v[242:243], off offset:512
	global_load_dword v239, v[242:243], off offset:576
	global_load_dword v240, v[242:243], off offset:640
	global_load_dword v241, v[242:243], off offset:704
	s_waitcnt vmcnt(0)
	v_cmp_gt_i32_e64 s[16:17], s1, v136
	v_mov_b32_e32 v164, 0
	v_mov_b32_e32 v168, 0
	s_and_saveexec_b64 s[2:3], s[16:17]
	s_cbranch_execz .LBB0_1424
	v_ashrrev_i32_e32 v137, 31, v136
	v_mov_b32_e32 v129, 0x358637bd
	s_mov_b32 s4, 0x800000
	v_fmac_f32_e32 v129, 0x39800000, v234
	v_mul_f32_e32 v128, 0x4b800000, v129
	v_cmp_gt_f32_e32 vcc, s4, v129
	s_nop 1
	v_cndmask_b32_e32 v128, v129, v128, vcc
	v_rsq_f32_e32 v128, v128
	s_nop 0
	v_mul_f32_e32 v129, 0x45800000, v128
	v_cndmask_b32_e32 v168, v128, v129, vcc
.LBB0_1424:
	s_or_b64 exec, exec, s[2:3]
	v_or_b32_e32 v166, 16, v136
	v_cmp_gt_i32_e64 s[14:15], s1, v166
	s_and_saveexec_b64 s[2:3], s[14:15]
	s_cbranch_execz .LBB0_1426
	v_ashrrev_i32_e32 v167, 31, v166
	v_mov_b32_e32 v129, 0x358637bd
	s_mov_b32 s1, 0x800000
	v_fmac_f32_e32 v129, 0x39800000, v235
	v_mul_f32_e32 v128, 0x4b800000, v129
	v_cmp_gt_f32_e32 vcc, s1, v129
	s_nop 1
	v_cndmask_b32_e32 v128, v129, v128, vcc
	v_rsq_f32_e32 v128, v128
	s_nop 0
	v_mul_f32_e32 v129, 0x45800000, v128
	v_cndmask_b32_e32 v164, v128, v129, vcc
.LBB0_1426:
	s_or_b64 exec, exec, s[2:3]
	v_or_b32_e32 v162, 32, v136
	s_movk_i32 s1, 0x2040
	v_cmp_gt_i32_e64 s[12:13], s1, v162
	v_mov_b32_e32 v156, 0
	v_mov_b32_e32 v160, 0
	s_and_saveexec_b64 s[2:3], s[12:13]
	s_cbranch_execz .LBB0_1428
	v_ashrrev_i32_e32 v163, 31, v162
	v_mov_b32_e32 v129, 0x358637bd
	s_mov_b32 s4, 0x800000
	v_fmac_f32_e32 v129, 0x39800000, v236
	v_mul_f32_e32 v128, 0x4b800000, v129
	v_cmp_gt_f32_e32 vcc, s4, v129
	s_nop 1
	v_cndmask_b32_e32 v128, v129, v128, vcc
	v_rsq_f32_e32 v128, v128
	s_nop 0
	v_mul_f32_e32 v129, 0x45800000, v128
	v_cndmask_b32_e32 v160, v128, v129, vcc
.LBB0_1428:
	s_or_b64 exec, exec, s[2:3]
	v_or_b32_e32 v158, 48, v136
	v_cmp_gt_i32_e64 s[10:11], s1, v158
	s_and_saveexec_b64 s[2:3], s[10:11]
	s_cbranch_execz .LBB0_1430
	v_ashrrev_i32_e32 v159, 31, v158
	v_mov_b32_e32 v129, 0x358637bd
	s_mov_b32 s1, 0x800000
	v_fmac_f32_e32 v129, 0x39800000, v237
	v_mul_f32_e32 v128, 0x4b800000, v129
	v_cmp_gt_f32_e32 vcc, s1, v129
	s_nop 1
	v_cndmask_b32_e32 v128, v129, v128, vcc
	v_rsq_f32_e32 v128, v128
	s_nop 0
	v_mul_f32_e32 v129, 0x45800000, v128
	v_cndmask_b32_e32 v156, v128, v129, vcc
.LBB0_1430:
	s_or_b64 exec, exec, s[2:3]
	s_movk_i32 s1, 0x1fc0
	v_add_u32_e32 v154, 0x80, v136
	v_cmp_gt_i32_e64 s[8:9], s1, v136
	v_mov_b32_e32 v148, 0
	v_mov_b32_e32 v152, 0
	s_and_saveexec_b64 s[2:3], s[8:9]
	s_cbranch_execz .LBB0_1432
	v_ashrrev_i32_e32 v155, 31, v154
	v_mov_b32_e32 v129, 0x358637bd
	s_mov_b32 s1, 0x800000
	v_fmac_f32_e32 v129, 0x39800000, v238
	v_mul_f32_e32 v128, 0x4b800000, v129
	v_cmp_gt_f32_e32 vcc, s1, v129
	s_nop 1
	v_cndmask_b32_e32 v128, v129, v128, vcc
	v_rsq_f32_e32 v128, v128
	s_nop 0
	v_mul_f32_e32 v129, 0x45800000, v128
	v_cndmask_b32_e32 v152, v128, v129, vcc
.LBB0_1432:
	s_or_b64 exec, exec, s[2:3]
	s_movk_i32 s1, 0x1fb0
	v_add_u32_e32 v150, 0x90, v136
	v_cmp_gt_i32_e64 s[6:7], s1, v136
	s_and_saveexec_b64 s[2:3], s[6:7]
	s_cbranch_execz .LBB0_1434
	v_ashrrev_i32_e32 v151, 31, v150
	v_mov_b32_e32 v129, 0x358637bd
	s_mov_b32 s1, 0x800000
	v_fmac_f32_e32 v129, 0x39800000, v239
	v_mul_f32_e32 v128, 0x4b800000, v129
	v_cmp_gt_f32_e32 vcc, s1, v129
	s_nop 1
	v_cndmask_b32_e32 v128, v129, v128, vcc
	v_rsq_f32_e32 v128, v128
	s_nop 0
	v_mul_f32_e32 v129, 0x45800000, v128
	v_cndmask_b32_e32 v148, v128, v129, vcc
.LBB0_1434:
	s_or_b64 exec, exec, s[2:3]
	s_movk_i32 s1, 0x1fa0
	v_add_u32_e32 v146, 0xa0, v136
	v_cmp_gt_i32_e64 s[4:5], s1, v136
	v_mov_b32_e32 v138, 0
	v_mov_b32_e32 v144, 0
	s_and_saveexec_b64 s[2:3], s[4:5]
	s_cbranch_execz .LBB0_1436
	v_ashrrev_i32_e32 v147, 31, v146
	v_mov_b32_e32 v129, 0x358637bd
	s_mov_b32 s1, 0x800000
	v_fmac_f32_e32 v129, 0x39800000, v240
	v_mul_f32_e32 v128, 0x4b800000, v129
	v_cmp_gt_f32_e32 vcc, s1, v129
	s_nop 1
	v_cndmask_b32_e32 v128, v129, v128, vcc
	v_rsq_f32_e32 v128, v128
	s_nop 0
	v_mul_f32_e32 v129, 0x45800000, v128
	v_cndmask_b32_e32 v144, v128, v129, vcc
.LBB0_1436:
	s_or_b64 exec, exec, s[2:3]
	s_movk_i32 s1, 0x1f90
	v_add_u32_e32 v142, 0xb0, v136
	v_cmp_gt_i32_e64 s[2:3], s1, v136
	s_and_saveexec_b64 s[18:19], s[2:3]
	s_cbranch_execz .LBB0_1438
	v_ashrrev_i32_e32 v143, 31, v142
	v_mov_b32_e32 v129, 0x358637bd
	s_mov_b32 s1, 0x800000
	v_fmac_f32_e32 v129, 0x39800000, v241
	v_mul_f32_e32 v128, 0x4b800000, v129
	v_cmp_gt_f32_e32 vcc, s1, v129
	s_nop 1
	v_cndmask_b32_e32 v128, v129, v128, vcc
	v_rsq_f32_e32 v128, v128
	s_nop 0
	v_mul_f32_e32 v129, 0x45800000, v128
	v_cndmask_b32_e32 v138, v128, v129, vcc

.LBB0_1793:
	s_or_b64 exec, exec, s[0:1]
	v_mov_b32_e32 v128, v244
	v_mov_b32_e32 v134, 0
	v_ashrrev_i32_e32 v129, 2, v128
	v_and_b32_e32 v129, 0xffffffc0, v129
	v_add_u32_e32 v129, s10, v129
	v_and_or_b32 v130, v128, 15, v129
	v_lshrrev_b32_e32 v129, 1, v128
	v_lshrrev_b32_e32 v128, 2, v128
	v_and_b32_e32 v129, 0x60, v129
	v_and_b32_e32 v128, 12, v128
	v_ashrrev_i32_e32 v131, 31, v130
	v_or3_b32 v128, v129, v128, s8
	v_lshlrev_b64 v[132:133], 13, v[130:131]
	v_cmp_gt_i32_e32 vcc, s25, v130
	v_lshl_add_u64 v[146:147], s[82:83], 0, v[132:133]
	v_mov_b32_e32 v132, 0
	v_ashrrev_i32_e32 v129, 31, v128
	v_mov_b32_e32 v135, 0
	v_mov_b32_e32 v136, 0
	v_mov_b32_e32 v137, 0
	v_lshlrev_b64 v[236:237], 1, v[128:129]
	v_mov_b32_e32 v238, v130
	v_ashrrev_i32_e32 v239, 31, v238
	v_lshlrev_b64 v[238:239], 13, v[238:239]
	v_lshl_add_u64 v[238:239], s[82:83], 0, v[238:239]
	v_lshl_add_u64 v[238:239], v[238:239], 0, v[236:237]
	global_load_dwordx2 v[204:205], v[238:239], off
	global_load_dwordx2 v[206:207], v[238:239], off offset:32
	global_load_dwordx2 v[208:209], v[238:239], off offset:256
	global_load_dwordx2 v[210:211], v[238:239], off offset:288
	v_add_u32_e32 v238, 0x10, v130
	v_ashrrev_i32_e32 v239, 31, v238
	v_lshlrev_b64 v[238:239], 13, v[238:239]
	v_lshl_add_u64 v[238:239], s[82:83], 0, v[238:239]
	v_lshl_add_u64 v[238:239], v[238:239], 0, v[236:237]
	global_load_dwordx2 v[212:213], v[238:239], off
	global_load_dwordx2 v[214:215], v[238:239], off offset:32
	global_load_dwordx2 v[216:217], v[238:239], off offset:256
	global_load_dwordx2 v[218:219], v[238:239], off offset:288
	v_add_u32_e32 v238, 0x20, v130
	v_ashrrev_i32_e32 v239, 31, v238
	v_lshlrev_b64 v[238:239], 13, v[238:239]
	v_lshl_add_u64 v[238:239], s[82:83], 0, v[238:239]
	v_lshl_add_u64 v[238:239], v[238:239], 0, v[236:237]
	global_load_dwordx2 v[220:221], v[238:239], off
	global_load_dwordx2 v[222:223], v[238:239], off offset:32
	global_load_dwordx2 v[224:225], v[238:239], off offset:256
	global_load_dwordx2 v[226:227], v[238:239], off offset:288
	v_add_u32_e32 v238, 0x30, v130
	v_ashrrev_i32_e32 v239, 31, v238
	v_lshlrev_b64 v[238:239], 13, v[238:239]
	v_lshl_add_u64 v[238:239], s[82:83], 0, v[238:239]
	v_lshl_add_u64 v[238:239], v[238:239], 0, v[236:237]
	global_load_dwordx2 v[228:229], v[238:239], off
	global_load_dwordx2 v[230:231], v[238:239], off offset:32
	global_load_dwordx2 v[232:233], v[238:239], off offset:256
	global_load_dwordx2 v[234:235], v[238:239], off offset:288
	s_waitcnt vmcnt(0)
	s_and_saveexec_b64 s[0:1], vcc
	s_cbranch_execz .LBB0_1795
	v_and_b32_e32 v135, 0xffff0000, v204
	v_and_b32_e32 v137, 0xffff0000, v205
	v_lshlrev_b32_e32 v134, 16, v204
	v_lshlrev_b32_e32 v136, 16, v205
.LBB0_1795:
	s_or_b64 exec, exec, s[0:1]
	v_mov_b32_e32 v133, 0
	v_mov_b32_e32 v140, 0
	v_mov_b32_e32 v141, 0
	s_and_saveexec_b64 s[0:1], vcc
	s_cbranch_execz .LBB0_1797
	v_and_b32_e32 v133, 0xffff0000, v206
	v_and_b32_e32 v141, 0xffff0000, v207
	v_lshlrev_b32_e32 v132, 16, v206
	v_lshlrev_b32_e32 v140, 16, v207
.LBB0_1797:
	s_or_b64 exec, exec, s[0:1]
	v_mov_b32_e32 v138, 0
	v_mov_b32_e32 v142, 0
	v_mov_b32_e32 v143, 0
	v_mov_b32_e32 v144, 0
	v_mov_b32_e32 v145, 0
	s_and_saveexec_b64 s[0:1], vcc
	s_cbranch_execz .LBB0_1799
	v_and_b32_e32 v143, 0xffff0000, v208
	v_and_b32_e32 v145, 0xffff0000, v209
	v_lshlrev_b32_e32 v142, 16, v208
	v_lshlrev_b32_e32 v144, 16, v209
.LBB0_1799:
	s_or_b64 exec, exec, s[0:1]
	v_mov_b32_e32 v139, 0
	v_mov_b32_e32 v148, 0
	v_mov_b32_e32 v149, 0
	s_and_saveexec_b64 s[0:1], vcc
	s_cbranch_execz .LBB0_1801
	v_and_b32_e32 v139, 0xffff0000, v210
	v_and_b32_e32 v149, 0xffff0000, v211
	v_lshlrev_b32_e32 v138, 16, v210
	v_lshlrev_b32_e32 v148, 16, v211
.LBB0_1801:
	s_or_b64 exec, exec, s[0:1]
	v_or_b32_e32 v150, 16, v130
	v_ashrrev_i32_e32 v151, 31, v150
	v_lshlrev_b64 v[146:147], 13, v[150:151]
	v_cmp_gt_i32_e64 s[0:1], s25, v150
	v_lshl_add_u64 v[164:165], s[82:83], 0, v[146:147]
	v_mov_b32_e32 v146, 0
	v_mov_b32_e32 v152, 0
	v_mov_b32_e32 v153, 0
	v_mov_b32_e32 v154, 0
	v_mov_b32_e32 v155, 0
	s_and_saveexec_b64 s[2:3], s[0:1]
	s_cbranch_execz .LBB0_1803
	v_and_b32_e32 v153, 0xffff0000, v212
	v_and_b32_e32 v155, 0xffff0000, v213
	v_lshlrev_b32_e32 v152, 16, v212
	v_lshlrev_b32_e32 v154, 16, v213
.LBB0_1803:
	s_or_b64 exec, exec, s[2:3]
	v_mov_b32_e32 v147, 0
	v_mov_b32_e32 v158, 0
	v_mov_b32_e32 v159, 0
	s_and_saveexec_b64 s[2:3], s[0:1]
	s_cbranch_execz .LBB0_1805
	v_and_b32_e32 v147, 0xffff0000, v214
	v_and_b32_e32 v159, 0xffff0000, v215
	v_lshlrev_b32_e32 v146, 16, v214
	v_lshlrev_b32_e32 v158, 16, v215
.LBB0_1805:
	s_or_b64 exec, exec, s[2:3]
	v_mov_b32_e32 v156, 0
	v_mov_b32_e32 v160, 0
	v_mov_b32_e32 v161, 0
	v_mov_b32_e32 v162, 0
	v_mov_b32_e32 v163, 0
	s_and_saveexec_b64 s[2:3], s[0:1]
	s_cbranch_execz .LBB0_1807
	v_and_b32_e32 v161, 0xffff0000, v216
	v_and_b32_e32 v163, 0xffff0000, v217
	v_lshlrev_b32_e32 v160, 16, v216
	v_lshlrev_b32_e32 v162, 16, v217
.LBB0_1807:
	s_or_b64 exec, exec, s[2:3]
	v_mov_b32_e32 v157, 0
	v_mov_b32_e32 v166, 0
	v_mov_b32_e32 v167, 0
	s_and_saveexec_b64 s[2:3], s[0:1]
	s_cbranch_execz .LBB0_1809
	v_and_b32_e32 v157, 0xffff0000, v218
	v_and_b32_e32 v167, 0xffff0000, v219
	v_lshlrev_b32_e32 v156, 16, v218
	v_lshlrev_b32_e32 v166, 16, v219
.LBB0_1809:
	s_or_b64 exec, exec, s[2:3]
	v_or_b32_e32 v168, 32, v130
	v_ashrrev_i32_e32 v169, 31, v168
	v_lshlrev_b64 v[164:165], 13, v[168:169]
	v_cmp_gt_i32_e64 s[2:3], s25, v168
	v_lshl_add_u64 v[182:183], s[82:83], 0, v[164:165]
	v_mov_b32_e32 v164, 0
	v_mov_b32_e32 v170, 0
	v_mov_b32_e32 v171, 0
	v_mov_b32_e32 v172, 0
	v_mov_b32_e32 v173, 0
	s_and_saveexec_b64 s[4:5], s[2:3]
	s_cbranch_execz .LBB0_1811
	v_and_b32_e32 v171, 0xffff0000, v220
	v_and_b32_e32 v173, 0xffff0000, v221
	v_lshlrev_b32_e32 v170, 16, v220
	v_lshlrev_b32_e32 v172, 16, v221
.LBB0_1811:
	s_or_b64 exec, exec, s[4:5]
	v_mov_b32_e32 v165, 0
	v_mov_b32_e32 v176, 0
	v_mov_b32_e32 v177, 0
	s_and_saveexec_b64 s[4:5], s[2:3]
	s_cbranch_execz .LBB0_1813
	v_and_b32_e32 v165, 0xffff0000, v222
	v_and_b32_e32 v177, 0xffff0000, v223
	v_lshlrev_b32_e32 v164, 16, v222
	v_lshlrev_b32_e32 v176, 16, v223
.LBB0_1813:
	s_or_b64 exec, exec, s[4:5]
	v_mov_b32_e32 v174, 0
	v_mov_b32_e32 v178, 0
	v_mov_b32_e32 v179, 0
	v_mov_b32_e32 v180, 0
	v_mov_b32_e32 v181, 0
	s_and_saveexec_b64 s[4:5], s[2:3]
	s_cbranch_execz .LBB0_1815
	v_and_b32_e32 v179, 0xffff0000, v224
	v_and_b32_e32 v181, 0xffff0000, v225
	v_lshlrev_b32_e32 v178, 16, v224
	v_lshlrev_b32_e32 v180, 16, v225
.LBB0_1815:
	s_or_b64 exec, exec, s[4:5]
	v_mov_b32_e32 v175, 0
	v_mov_b32_e32 v184, 0
	v_mov_b32_e32 v185, 0
	s_and_saveexec_b64 s[4:5], s[2:3]
	s_cbranch_execz .LBB0_1817
	v_and_b32_e32 v175, 0xffff0000, v226
	v_and_b32_e32 v185, 0xffff0000, v227
	v_lshlrev_b32_e32 v174, 16, v226
	v_lshlrev_b32_e32 v184, 16, v227
.LBB0_1817:
	s_or_b64 exec, exec, s[4:5]
	v_or_b32_e32 v186, 48, v130
	v_ashrrev_i32_e32 v187, 31, v186
	v_lshlrev_b64 v[182:183], 13, v[186:187]
	v_cmp_gt_i32_e64 s[4:5], s25, v186
	v_lshl_add_u64 v[202:203], s[82:83], 0, v[182:183]
	v_mov_b32_e32 v182, 0
	v_mov_b32_e32 v188, 0
	v_mov_b32_e32 v189, 0
	v_mov_b32_e32 v190, 0
	v_mov_b32_e32 v191, 0
	s_and_saveexec_b64 s[8:9], s[4:5]
	s_cbranch_execz .LBB0_1819
	v_and_b32_e32 v189, 0xffff0000, v228
	v_and_b32_e32 v191, 0xffff0000, v229
	v_lshlrev_b32_e32 v188, 16, v228
	v_lshlrev_b32_e32 v190, 16, v229
.LBB0_1819:
	s_or_b64 exec, exec, s[8:9]
	v_mov_b32_e32 v183, 0
	v_mov_b32_e32 v194, 0
	v_mov_b32_e32 v195, 0
	s_and_saveexec_b64 s[8:9], s[4:5]
	s_cbranch_execz .LBB0_1821
	v_and_b32_e32 v183, 0xffff0000, v230
	v_and_b32_e32 v195, 0xffff0000, v231
	v_lshlrev_b32_e32 v182, 16, v230
	v_lshlrev_b32_e32 v194, 16, v231
.LBB0_1821:
	s_or_b64 exec, exec, s[8:9]
	v_mov_b32_e32 v192, 0
	v_mov_b32_e32 v196, 0
	v_mov_b32_e32 v197, 0
	v_mov_b32_e32 v198, 0
	v_mov_b32_e32 v199, 0
	s_and_saveexec_b64 s[8:9], s[4:5]
	s_cbranch_execz .LBB0_1823
	v_and_b32_e32 v197, 0xffff0000, v232
	v_and_b32_e32 v199, 0xffff0000, v233
	v_lshlrev_b32_e32 v196, 16, v232
	v_lshlrev_b32_e32 v198, 16, v233
.LBB0_1823:
	s_or_b64 exec, exec, s[8:9]
	v_mov_b32_e32 v193, 0
	v_mov_b32_e32 v200, 0
	v_mov_b32_e32 v201, 0
	s_and_saveexec_b64 s[8:9], s[4:5]
	s_cbranch_execz .LBB0_1864
	v_and_b32_e32 v193, 0xffff0000, v234
	v_and_b32_e32 v201, 0xffff0000, v235
	v_lshlrev_b32_e32 v192, 16, v234
	v_lshlrev_b32_e32 v200, 16, v235
	s_or_b64 exec, exec, s[8:9]
	s_and_saveexec_b64 s[8:9], vcc
	s_cbranch_execnz .LBB0_1865

.LBB0_1829:
	s_or_b64 exec, exec, s[0:1]
	s_nop 0
	v_add_u32_e32 v66, 0x80, v130
	v_ashrrev_i32_e32 v67, 31, v66
	v_lshlrev_b64 v[64:65], 13, v[66:67]
	v_cmp_gt_i32_e32 vcc, s26, v130
	v_lshl_add_u64 v[80:81], s[82:83], 0, v[64:65]
	v_mov_b32_e32 v64, 0
	v_mov_b32_e32 v68, 0
	v_mov_b32_e32 v69, 0
	v_mov_b32_e32 v70, 0
	v_mov_b32_e32 v71, 0
	v_lshlrev_b64 v[236:237], 1, v[128:129]
	v_add_u32_e32 v238, 0x80, v130
	v_ashrrev_i32_e32 v239, 31, v238
	v_lshlrev_b64 v[238:239], 13, v[238:239]
	v_lshl_add_u64 v[238:239], s[82:83], 0, v[238:239]
	v_lshl_add_u64 v[238:239], v[238:239], 0, v[236:237]
	global_load_dwordx2 v[204:205], v[238:239], off
	global_load_dwordx2 v[206:207], v[238:239], off offset:32
	global_load_dwordx2 v[208:209], v[238:239], off offset:256
	global_load_dwordx2 v[210:211], v[238:239], off offset:288
	v_add_u32_e32 v238, 0x90, v130
	v_ashrrev_i32_e32 v239, 31, v238
	v_lshlrev_b64 v[238:239], 13, v[238:239]
	v_lshl_add_u64 v[238:239], s[82:83], 0, v[238:239]
	v_lshl_add_u64 v[238:239], v[238:239], 0, v[236:237]
	global_load_dwordx2 v[212:213], v[238:239], off
	global_load_dwordx2 v[214:215], v[238:239], off offset:32
	global_load_dwordx2 v[216:217], v[238:239], off offset:256
	global_load_dwordx2 v[218:219], v[238:239], off offset:288
	v_add_u32_e32 v238, 0xa0, v130
	v_ashrrev_i32_e32 v239, 31, v238
	v_lshlrev_b64 v[238:239], 13, v[238:239]
	v_lshl_add_u64 v[238:239], s[82:83], 0, v[238:239]
	v_lshl_add_u64 v[238:239], v[238:239], 0, v[236:237]
	global_load_dwordx2 v[220:221], v[238:239], off
	global_load_dwordx2 v[222:223], v[238:239], off offset:32
	global_load_dwordx2 v[224:225], v[238:239], off offset:256
	global_load_dwordx2 v[226:227], v[238:239], off offset:288
	v_add_u32_e32 v238, 0xb0, v130
	v_ashrrev_i32_e32 v239, 31, v238
	v_lshlrev_b64 v[238:239], 13, v[238:239]
	v_lshl_add_u64 v[238:239], s[82:83], 0, v[238:239]
	v_lshl_add_u64 v[238:239], v[238:239], 0, v[236:237]
	global_load_dwordx2 v[228:229], v[238:239], off
	global_load_dwordx2 v[230:231], v[238:239], off offset:32
	global_load_dwordx2 v[232:233], v[238:239], off offset:256
	global_load_dwordx2 v[234:235], v[238:239], off offset:288
	s_waitcnt vmcnt(0)
	s_and_saveexec_b64 s[0:1], vcc
	s_cbranch_execz .LBB0_1831
	v_and_b32_e32 v69, 0xffff0000, v204
	v_and_b32_e32 v71, 0xffff0000, v205
	v_lshlrev_b32_e32 v68, 16, v204
	v_lshlrev_b32_e32 v70, 16, v205
.LBB0_1831:
	s_or_b64 exec, exec, s[0:1]
	v_mov_b32_e32 v65, 0
	v_mov_b32_e32 v74, 0
	v_mov_b32_e32 v75, 0
	s_and_saveexec_b64 s[0:1], vcc
	s_cbranch_execz .LBB0_1833
	v_and_b32_e32 v65, 0xffff0000, v206
	v_and_b32_e32 v75, 0xffff0000, v207
	v_lshlrev_b32_e32 v64, 16, v206
	v_lshlrev_b32_e32 v74, 16, v207
.LBB0_1833:
	s_or_b64 exec, exec, s[0:1]
	v_mov_b32_e32 v72, 0
	v_mov_b32_e32 v76, 0
	v_mov_b32_e32 v77, 0
	v_mov_b32_e32 v78, 0
	v_mov_b32_e32 v79, 0
	s_and_saveexec_b64 s[0:1], vcc
	s_cbranch_execz .LBB0_1835
	v_and_b32_e32 v77, 0xffff0000, v208
	v_and_b32_e32 v79, 0xffff0000, v209
	v_lshlrev_b32_e32 v76, 16, v208
	v_lshlrev_b32_e32 v78, 16, v209
.LBB0_1835:
	s_or_b64 exec, exec, s[0:1]
	v_mov_b32_e32 v73, 0
	v_mov_b32_e32 v82, 0
	v_mov_b32_e32 v83, 0
	s_and_saveexec_b64 s[0:1], vcc
	s_cbranch_execz .LBB0_1837
	v_and_b32_e32 v73, 0xffff0000, v210
	v_and_b32_e32 v83, 0xffff0000, v211
	v_lshlrev_b32_e32 v72, 16, v210
	v_lshlrev_b32_e32 v82, 16, v211
.LBB0_1837:
	s_or_b64 exec, exec, s[0:1]
	v_add_u32_e32 v84, 0x90, v130
	v_ashrrev_i32_e32 v85, 31, v84
	v_lshlrev_b64 v[80:81], 13, v[84:85]
	v_cmp_gt_i32_e64 s[0:1], s27, v130
	v_lshl_add_u64 v[98:99], s[82:83], 0, v[80:81]
	v_mov_b32_e32 v80, 0
	v_mov_b32_e32 v86, 0
	v_mov_b32_e32 v87, 0
	v_mov_b32_e32 v88, 0
	v_mov_b32_e32 v89, 0
	s_and_saveexec_b64 s[2:3], s[0:1]
	s_cbranch_execz .LBB0_1839
	v_and_b32_e32 v87, 0xffff0000, v212
	v_and_b32_e32 v89, 0xffff0000, v213
	v_lshlrev_b32_e32 v86, 16, v212
	v_lshlrev_b32_e32 v88, 16, v213
.LBB0_1839:
	s_or_b64 exec, exec, s[2:3]
	v_mov_b32_e32 v81, 0
	v_mov_b32_e32 v92, 0
	v_mov_b32_e32 v93, 0
	s_and_saveexec_b64 s[2:3], s[0:1]
	s_cbranch_execz .LBB0_1841
	v_and_b32_e32 v81, 0xffff0000, v214
	v_and_b32_e32 v93, 0xffff0000, v215
	v_lshlrev_b32_e32 v80, 16, v214
	v_lshlrev_b32_e32 v92, 16, v215
.LBB0_1841:
	s_or_b64 exec, exec, s[2:3]
	v_mov_b32_e32 v90, 0
	v_mov_b32_e32 v94, 0
	v_mov_b32_e32 v95, 0
	v_mov_b32_e32 v96, 0
	v_mov_b32_e32 v97, 0
	s_and_saveexec_b64 s[2:3], s[0:1]
	s_cbranch_execz .LBB0_1843
	v_and_b32_e32 v95, 0xffff0000, v216
	v_and_b32_e32 v97, 0xffff0000, v217
	v_lshlrev_b32_e32 v94, 16, v216
	v_lshlrev_b32_e32 v96, 16, v217
.LBB0_1843:
	s_or_b64 exec, exec, s[2:3]
	v_mov_b32_e32 v91, 0
	v_mov_b32_e32 v100, 0
	v_mov_b32_e32 v101, 0
	s_and_saveexec_b64 s[2:3], s[0:1]
	s_cbranch_execz .LBB0_1845
	v_and_b32_e32 v91, 0xffff0000, v218
	v_and_b32_e32 v101, 0xffff0000, v219
	v_lshlrev_b32_e32 v90, 16, v218
	v_lshlrev_b32_e32 v100, 16, v219
.LBB0_1845:
	s_or_b64 exec, exec, s[2:3]
	v_add_u32_e32 v102, 0xa0, v130
	v_ashrrev_i32_e32 v103, 31, v102
	v_lshlrev_b64 v[98:99], 13, v[102:103]
	v_cmp_gt_i32_e64 s[2:3], s28, v130
	v_lshl_add_u64 v[116:117], s[82:83], 0, v[98:99]
	v_mov_b32_e32 v98, 0
	v_mov_b32_e32 v104, 0
	v_mov_b32_e32 v105, 0
	v_mov_b32_e32 v106, 0
	v_mov_b32_e32 v107, 0
	s_and_saveexec_b64 s[4:5], s[2:3]
	s_cbranch_execz .LBB0_1847
	v_and_b32_e32 v105, 0xffff0000, v220
	v_and_b32_e32 v107, 0xffff0000, v221
	v_lshlrev_b32_e32 v104, 16, v220
	v_lshlrev_b32_e32 v106, 16, v221
.LBB0_1847:
	s_or_b64 exec, exec, s[4:5]
	v_mov_b32_e32 v99, 0
	v_mov_b32_e32 v110, 0
	v_mov_b32_e32 v111, 0
	s_and_saveexec_b64 s[4:5], s[2:3]
	s_cbranch_execz .LBB0_1849
	v_and_b32_e32 v99, 0xffff0000, v222
	v_and_b32_e32 v111, 0xffff0000, v223
	v_lshlrev_b32_e32 v98, 16, v222
	v_lshlrev_b32_e32 v110, 16, v223
.LBB0_1849:
	s_or_b64 exec, exec, s[4:5]
	v_mov_b32_e32 v108, 0
	v_mov_b32_e32 v112, 0
	v_mov_b32_e32 v113, 0
	v_mov_b32_e32 v114, 0
	v_mov_b32_e32 v115, 0
	s_and_saveexec_b64 s[4:5], s[2:3]
	s_cbranch_execz .LBB0_1851
	v_and_b32_e32 v113, 0xffff0000, v224
	v_and_b32_e32 v115, 0xffff0000, v225
	v_lshlrev_b32_e32 v112, 16, v224
	v_lshlrev_b32_e32 v114, 16, v225
.LBB0_1851:
	s_or_b64 exec, exec, s[4:5]
	v_mov_b32_e32 v109, 0
	v_mov_b32_e32 v118, 0
	v_mov_b32_e32 v119, 0
	s_and_saveexec_b64 s[4:5], s[2:3]
	s_cbranch_execz .LBB0_1853
	v_and_b32_e32 v109, 0xffff0000, v226
	v_and_b32_e32 v119, 0xffff0000, v227
	v_lshlrev_b32_e32 v108, 16, v226
	v_lshlrev_b32_e32 v118, 16, v227
.LBB0_1853:
	s_or_b64 exec, exec, s[4:5]
	v_add_u32_e32 v120, 0xb0, v130
	v_ashrrev_i32_e32 v121, 31, v120
	v_lshlrev_b64 v[116:117], 13, v[120:121]
	v_cmp_gt_i32_e64 s[4:5], s29, v130
	v_lshl_add_u64 v[138:139], s[82:83], 0, v[116:117]
	v_mov_b32_e32 v116, 0
	v_mov_b32_e32 v122, 0
	v_mov_b32_e32 v123, 0
	v_mov_b32_e32 v124, 0
	v_mov_b32_e32 v125, 0
	s_and_saveexec_b64 s[8:9], s[4:5]
	s_cbranch_execz .LBB0_1855
	v_and_b32_e32 v123, 0xffff0000, v228
	v_and_b32_e32 v125, 0xffff0000, v229
	v_lshlrev_b32_e32 v122, 16, v228
	v_lshlrev_b32_e32 v124, 16, v229
.LBB0_1855:
	s_or_b64 exec, exec, s[8:9]
	v_mov_b32_e32 v117, 0
	v_mov_b32_e32 v130, 0
	v_mov_b32_e32 v131, 0
	s_and_saveexec_b64 s[8:9], s[4:5]
	s_cbranch_execz .LBB0_1857
	v_and_b32_e32 v117, 0xffff0000, v230
	v_and_b32_e32 v131, 0xffff0000, v231
	v_lshlrev_b32_e32 v116, 16, v230
	v_lshlrev_b32_e32 v130, 16, v231
.LBB0_1857:
	s_or_b64 exec, exec, s[8:9]
	v_mov_b32_e32 v126, 0
	v_mov_b32_e32 v132, 0
	v_mov_b32_e32 v133, 0
	v_mov_b32_e32 v134, 0
	v_mov_b32_e32 v135, 0
	s_and_saveexec_b64 s[8:9], s[4:5]
	s_cbranch_execz .LBB0_1859
	v_and_b32_e32 v133, 0xffff0000, v232
	v_and_b32_e32 v135, 0xffff0000, v233
	v_lshlrev_b32_e32 v132, 16, v232
	v_lshlrev_b32_e32 v134, 16, v233
.LBB0_1859:
	s_or_b64 exec, exec, s[8:9]
	v_mov_b32_e32 v127, 0
	v_mov_b32_e32 v136, 0
	v_mov_b32_e32 v137, 0
	s_and_saveexec_b64 s[8:9], s[4:5]
	s_cbranch_execz .LBB0_1868
	v_and_b32_e32 v127, 0xffff0000, v234
	v_and_b32_e32 v137, 0xffff0000, v235
	v_lshlrev_b32_e32 v126, 16, v234
	v_lshlrev_b32_e32 v136, 16, v235
	s_or_b64 exec, exec, s[8:9]
	s_and_saveexec_b64 s[8:9], vcc
	s_cbranch_execnz .LBB0_1869
